# MLA fixed-shift loop: V tile load issued at the loop top into its own staging registers (was mid-body behind the K read buffers): a full iteration of cover
# speedup vs baseline: 1.0139x; 1.0071x over previous
.LBB0_1186:
	s_or_b64 exec, exec, s[2:3]
	v_lshlrev_b64 v[2:3], 6, v[24:25]
	v_lshlrev_b32_e32 v4, 3, v32
	v_lshl_add_u64 v[2:3], v[2:3], 1, v[12:13]
	v_lshlrev_b32_e32 v4, 1, v4
	v_mov_b32_e32 v5, v113
	v_lshl_add_u64 v[2:3], v[2:3], 0, v[4:5]
	v_add_co_u32_e32 v2, vcc, 0x2000, v2
	v_and_b32_e32 v6, 31, v29
	s_nop 0
	v_addc_co_u32_e32 v3, vcc, 0, v3, vcc
	global_load_dwordx4 v[204:207], v[2:3], off
	v_mul_u32_u24_e32 v2, 0xd0, v6
	v_add3_u32 v180, 0, v2, v22
	s_waitcnt lgkmcnt(0)
	s_barrier
	ds_read_b128 v[2:5], v180
	ds_read_b128 v[12:15], v180 offset:32
	v_xor_b32_e32 v32, 0x80000000, v28
	v_mov_b32_e32 v33, v32
	v_mov_b32_e32 v34, v32
	v_mov_b32_e32 v35, v32
	v_mov_b32_e32 v36, v32
	v_mov_b32_e32 v37, v32
	v_mov_b32_e32 v38, v32
	v_mov_b32_e32 v39, v32
	v_mov_b32_e32 v40, v32
	v_mov_b32_e32 v41, v32
	v_mov_b32_e32 v42, v32
	v_mov_b32_e32 v43, v32
	v_mov_b32_e32 v44, v32
	v_mov_b32_e32 v45, v32
	v_mov_b32_e32 v46, v32
	v_mov_b32_e32 v47, v32
	v_lshl_add_u64 v[0:1], v[0:1], 0, v[10:11]
	v_lshl_add_u64 v[0:1], v[18:19], 1, v[0:1]
	s_waitcnt lgkmcnt(0)
	v_mfma_f32_32x32x16_bf16 v[64:79], v[2:5], v[100:103], v[32:47]
	ds_read_b128 v[2:5], v180 offset:6656
	ds_read_b128 v[24:27], v180 offset:6688
	v_lshl_add_u64 v[142:143], s[12:13], 0, v[0:1]
	v_mad_i64_i32 v[0:1], s[2:3], v23, s22, v[10:11]
	v_lshlrev_b32_e32 v177, 2, v30
	v_lshrrev_b32_e32 v6, 2, v29
	v_lshl_add_u64 v[0:1], v[16:17], 1, v[0:1]
	s_waitcnt lgkmcnt(0)
	v_mfma_f32_32x32x16_bf16 v[48:63], v[2:5], v[100:103], v[32:47]
	v_and_or_b32 v6, v6, 3, v177
	v_lshlrev_b32_e32 v7, 1, v29
	v_lshl_add_u64 v[162:163], s[12:13], 0, v[0:1]
	v_lshl_add_u64 v[0:1], v[8:9], 0, v[20:21]
	v_mad_u32_u24 v6, v6, s20, 0
	v_and_b32_e32 v7, 32, v7
	v_lshl_add_u64 v[0:1], v[0:1], 0, v[112:113]
	v_mfma_f32_32x32x16_bf16 v[64:79], v[12:15], v[104:107], v[64:79]
	ds_read_b128 v[2:5], v180 offset:64
	ds_read_b128 v[12:15], v180 offset:96
	v_mov_b32_e32 v114, 0
	v_and_b32_e32 v178, 63, v29
	s_mov_b32 s34, 0
	v_add_u32_e32 v173, -3, v166
	v_lshl_add_u64 v[164:165], s[14:15], 0, v[0:1]
	s_mov_b64 s[2:3], 0
	v_mfma_f32_32x32x16_bf16 v[48:63], v[24:27], v[104:107], v[48:63]
	v_mov_b32_e32 v0, 0
	v_mov_b32_e32 v1, v114
	v_mov_b32_e32 v8, v114
	v_mov_b32_e32 v9, v114
	v_mov_b32_e32 v10, v114
	v_mov_b32_e32 v11, v114
	v_mov_b32_e32 v16, 0
	s_waitcnt lgkmcnt(0)
	v_mfma_f32_32x32x16_bf16 v[64:79], v[2:5], v[108:111], v[64:79]
	ds_read_b128 v[2:5], v180 offset:6720
	ds_read_b128 v[24:27], v180 offset:6752
	v_mov_b32_e32 v17, v114
	v_mov_b32_e32 v18, v114
	v_mov_b32_e32 v19, v114
	v_mov_b32_e32 v20, v114
	v_mov_b32_e32 v21, v114
	v_mov_b32_e32 v22, v114
	s_waitcnt lgkmcnt(0)
	v_mfma_f32_32x32x16_bf16 v[48:63], v[2:5], v[108:111], v[48:63]
	ds_read_b128 v[2:5], v180 offset:128
	ds_read_b128 v[80:83], v180 offset:160
	ds_read_b128 v[84:87], v180 offset:6784
	ds_read_b128 v[88:91], v180 offset:6816
	v_mov_b32_e32 v23, v114
	v_mov_b32_e32 v28, v114
	v_mov_b32_e32 v30, v114
	v_mov_b32_e32 v31, v114
	s_waitcnt lgkmcnt(0)
	s_barrier
	v_mfma_f32_32x32x16_bf16 v[64:79], v[12:15], v[116:119], v[64:79]
	v_lshlrev_b32_e32 v12, 3, v29
	v_and_b32_e32 v12, 24, v12
	v_add3_u32 v179, v6, v7, v12
	v_mov_b32_e32 v6, v114
	v_mov_b32_e32 v7, v114
	v_mov_b32_e32 v12, v114
	v_mov_b32_e32 v13, v114
	v_mfma_f32_32x32x16_bf16 v[48:63], v[24:27], v[116:119], v[48:63]
	v_mov_b32_e32 v14, v114
	v_mov_b32_e32 v15, v114
	v_mov_b32_e32 v24, v114
	v_mov_b32_e32 v25, v114
	v_mov_b32_e32 v26, v114
	v_mov_b32_e32 v27, v114
	v_mov_b32_e32 v29, v114
	v_mfma_f32_32x32x16_bf16 v[64:79], v[2:5], v[120:123], v[64:79]
	v_mov_b32_e32 v2, v114
	v_mov_b32_e32 v3, v114
	v_mov_b32_e32 v4, v114
	v_mov_b32_e32 v5, v114
	v_mfma_f32_32x32x16_bf16 v[48:63], v[84:87], v[120:123], v[48:63]
	v_mfma_f32_32x32x16_bf16 v[64:79], v[80:83], v[96:99], v[64:79]
	v_mfma_f32_32x32x16_bf16 v[48:63], v[88:91], v[96:99], v[48:63]
	s_branch .LBB0_1188
.LBB0_1187:
	s_or_b64 exec, exec, s[36:37]
	s_add_i32 s34, s34, 1
	s_bitcmp1_b32 s34, 0
	s_cselect_b32 s36, 0x3400, 0
	v_add_u32_e32 v112, s36, v180
	ds_read_b128 v[132:135], v112
	ds_read_b128 v[136:139], v112 offset:32
	v_exp_f32_e32 v174, v48
	v_exp_f32_e32 v175, v49
	v_exp_f32_e32 v182, v50
	s_waitcnt lgkmcnt(0)
	v_mfma_f32_32x32x16_bf16 v[80:95], v[132:135], v[100:103], v[32:47]
	v_exp_f32_e32 v183, v51
	v_exp_f32_e32 v184, v52
	v_exp_f32_e32 v185, v53
	v_exp_f32_e32 v186, v54
	v_exp_f32_e32 v187, v55
	v_exp_f32_e32 v188, v56
	v_exp_f32_e32 v189, v57
	v_mfma_f32_32x32x16_bf16 v[80:95], v[136:139], v[104:107], v[80:95]
	ds_read_b128 v[132:135], v112 offset:64
	ds_read_b128 v[136:139], v112 offset:96
	v_exp_f32_e32 v190, v58
	v_exp_f32_e32 v191, v59
	v_exp_f32_e32 v192, v60
	v_exp_f32_e32 v193, v61
	v_exp_f32_e32 v194, v62
	v_exp_f32_e32 v195, v63
	s_waitcnt lgkmcnt(0)
	v_mfma_f32_32x32x16_bf16 v[80:95], v[132:135], v[108:111], v[80:95]
	ds_read_b128 v[132:135], v112 offset:128
	ds_read_b128 v[48:51], v112 offset:160
	s_and_b64 s[18:19], s[18:19], exec
	s_cselect_b32 s18, 0x2400, 0
	v_exp_f32_e32 v198, v64
	v_exp_f32_e32 v199, v65
	v_exp_f32_e32 v200, v70
	v_mfma_f32_32x32x16_bf16 v[80:95], v[136:139], v[116:119], v[80:95]
	v_exp_f32_e32 v201, v71
	v_exp_f32_e32 v202, v72
	v_exp_f32_e32 v203, v73
	v_exp_f32_e32 v76, v76
	v_cvt_pk_bf16_f32 v71, v200, v201
	v_exp_f32_e32 v78, v78
	v_exp_f32_e32 v79, v79
	s_waitcnt lgkmcnt(0)
	v_mfma_f32_32x32x16_bf16 v[80:95], v[132:135], v[120:123], v[80:95]
	ds_read_b128 v[132:135], v112 offset:6656
	ds_read_b128 v[146:149], v112 offset:6688
	v_exp_f32_e32 v77, v77
	v_cmp_eq_u32_e32 vcc, s34, v173
	v_lshl_add_u64 v[142:143], v[142:143], 0, s[24:25]
	v_lshl_add_u64 v[162:163], v[162:163], 0, s[24:25]
	s_or_b64 s[2:3], vcc, s[2:3]
	v_mfma_f32_32x32x16_bf16 v[80:95], v[48:51], v[96:99], v[80:95]
	s_waitcnt lgkmcnt(0)
	v_mfma_f32_32x32x16_bf16 v[48:63], v[132:135], v[100:103], v[32:47]
	ds_read_b128 v[150:153], v112 offset:6720
	ds_read_b128 v[154:157], v112 offset:6752
	ds_read_b128 v[158:161], v112 offset:6784
	ds_read_b128 v[136:139], v112 offset:6816
	v_add_u32_e32 v112, s18, v179
	v_lshl_add_u64 v[164:165], v[164:165], 0, s[0:1]
	v_mfma_f32_32x32x16_bf16 v[48:63], v[146:149], v[104:107], v[48:63]
	v_exp_f32_e32 v146, v66
	v_exp_f32_e32 v147, v67
	v_exp_f32_e32 v148, v68
	v_exp_f32_e32 v149, v69
	ds_read_b64_tr_b16 v[64:65], v112 offset:26624
	ds_read_b64_tr_b16 v[66:67], v112 offset:27776
	v_cvt_pk_bf16_f32 v68, v198, v199
	v_cvt_pk_bf16_f32 v69, v146, v147
	s_waitcnt lgkmcnt(0)
	v_mfma_f32_32x32x16_bf16 v[48:63], v[150:153], v[108:111], v[48:63]
	v_exp_f32_e32 v150, v74
	v_exp_f32_e32 v151, v75
	ds_read_b64_tr_b16 v[74:75], v112 offset:27840
	ds_read_b64_tr_b16 v[72:73], v112 offset:26688
	v_cvt_pk_bf16_f32 v70, v148, v149
	v_pk_add_f32 v[146:147], v[182:183], v[146:147]
	v_pk_add_f32 v[198:199], v[174:175], v[198:199]
	v_pk_add_f32 v[148:149], v[184:185], v[148:149]
	v_mfma_f32_32x32x16_bf16 v[0:15], v[64:67], v[68:71], v[0:15]
	ds_read_b64_tr_b16 v[64:65], v112 offset:28928
	ds_read_b64_tr_b16 v[66:67], v112 offset:30080
	v_add_f32_e64 v152, v194, v78
	v_add_f32_e64 v153, v195, v79
	s_waitcnt lgkmcnt(0)
	v_mfma_f32_32x32x16_bf16 v[16:31], v[72:75], v[68:71], v[16:31]
	ds_read_b64_tr_b16 v[74:75], v112 offset:30144
	ds_read_b64_tr_b16 v[72:73], v112 offset:28992
	v_cvt_pk_bf16_f32 v68, v202, v203
	v_cvt_pk_bf16_f32 v69, v150, v151
	v_cvt_pk_bf16_f32 v70, v76, v77
	v_cvt_pk_bf16_f32 v71, v78, v79
	v_mfma_f32_32x32x16_bf16 v[48:63], v[154:157], v[116:119], v[48:63]
	v_add_f32_e64 v154, v192, v76
	v_add_f32_e64 v155, v193, v77
	v_add_f32_e64 v156, v190, v150
	v_add_f32_e64 v157, v191, v151
	v_mfma_f32_32x32x16_bf16 v[0:15], v[64:67], v[68:71], v[0:15]
	s_waitcnt lgkmcnt(0)
	v_mfma_f32_32x32x16_bf16 v[16:31], v[72:75], v[68:71], v[16:31]
	v_cvt_pk_bf16_f32 v68, v174, v175
	v_cvt_pk_bf16_f32 v69, v182, v183
	v_cvt_pk_bf16_f32 v70, v184, v185
	v_cvt_pk_bf16_f32 v71, v186, v187
	v_mfma_f32_32x32x16_bf16 v[48:63], v[158:161], v[120:123], v[48:63]
	v_add_f32_e64 v160, v186, v200
	v_add_f32_e64 v161, v187, v201
	v_pk_mov_b32 v[200:201], v[198:199], v[146:147] op_sel:[1,0]
	v_mov_b32_e32 v199, v147
	v_pk_add_f32 v[64:65], v[200:201], v[198:199]
	v_pk_mov_b32 v[78:79], v[148:149], v[160:161] op_sel:[1,0]
	v_pk_add_f32 v[76:77], v[64:65], v[64:65] op_sel_hi:[0,1]
	ds_read_b64_tr_b16 v[64:65], v112 offset:31232
	ds_read_b64_tr_b16 v[66:67], v112 offset:32384
	ds_read_b64_tr_b16 v[74:75], v112 offset:32448
	ds_read_b64_tr_b16 v[72:73], v112 offset:31296
	s_waitcnt lgkmcnt(0)
	v_mfma_f32_32x32x16_bf16 v[0:15], v[64:67], v[68:71], v[0:15]
	ds_read_b64_tr_b16 v[64:65], v112 offset:33536
	ds_read_b64_tr_b16 v[66:67], v112 offset:34688
	v_mov_b32_e32 v149, v161
	v_add_f32_e64 v78, v78, v148
	v_add_f32_e64 v79, v79, v149
	v_pk_add_f32 v[158:159], v[188:189], v[202:203]
	v_pk_add_f32 v[78:79], v[78:79], v[78:79] op_sel_hi:[0,1]
	v_add_f32_e32 v147, v158, v159
	v_add_f32_e32 v149, v156, v157
	v_mfma_f32_32x32x16_bf16 v[16:31], v[72:75], v[68:71], v[16:31]
	ds_read_b64_tr_b16 v[74:75], v112 offset:34752
	ds_read_b64_tr_b16 v[72:73], v112 offset:33600
	v_cvt_pk_bf16_f32 v68, v188, v189
	v_cvt_pk_bf16_f32 v69, v190, v191
	v_cvt_pk_bf16_f32 v70, v192, v193
	v_cvt_pk_bf16_f32 v71, v194, v195
	v_mov_b32_e32 v146, v154
	v_mov_b32_e32 v148, v155
	s_waitcnt lgkmcnt(0)
	v_mfma_f32_32x32x16_bf16 v[0:15], v[64:67], v[68:71], v[0:15]
	v_mov_b32_e32 v76, v152
	v_mov_b32_e32 v78, v153
	v_add_f32_e64 v146, v146, v148
	v_add_f32_e64 v147, v147, v149
	v_add_f32_e64 v64, v76, v78
	v_add_f32_e64 v65, v77, v79
	v_pk_add_f32 v[64:65], v[146:147], v[64:65]
	s_barrier
	v_mfma_f32_32x32x16_bf16 v[16:31], v[72:75], v[68:71], v[16:31]
	v_add_f32_e32 v64, v64, v65
	v_add_f32_e32 v114, v114, v64
	v_mov_b64_e32 v[64:65], v[80:81]
	v_mov_b64_e32 v[66:67], v[82:83]
	v_mov_b64_e32 v[68:69], v[84:85]
	v_mov_b64_e32 v[70:71], v[86:87]
	v_mov_b64_e32 v[72:73], v[88:89]
	v_mfma_f32_32x32x16_bf16 v[48:63], v[136:139], v[96:99], v[48:63]
	v_mov_b64_e32 v[74:75], v[90:91]
	v_mov_b64_e32 v[76:77], v[92:93]
	v_mov_b64_e32 v[78:79], v[94:95]
	s_andn2_b64 exec, exec, s[2:3]
	s_cbranch_execz .LBB0_1192
.LBB0_1188:
	s_bitcmp1_b32 s34, 0
	s_cselect_b64 s[18:19], -1, 0
	s_and_b64 s[36:37], s[18:19], exec
	s_cselect_b32 s36, 0x3400, 0
	s_add_i32 s46, s36, 0
	v_add3_u32 v80, s46, v168, v170
	s_waitcnt vmcnt(0)
	ds_write_b128 v80, v[128:131]
	s_and_saveexec_b64 s[36:37], s[6:7]
	v_add3_u32 v80, s46, v171, v172
	ds_write_b128 v80, v[124:127]
	s_or_b64 exec, exec, s[36:37]
	s_andn2_b32 s36, 1, s34
	s_mulk_i32 s36, 0x2400
	v_add_u32_e32 v80, s36, v115
	ds_write_b128 v80, v[204:207] offset:26624
	global_load_dwordx4 v[204:207], v[164:165], off
	global_load_dwordx4 v[128:131], v[162:163], off
	s_and_saveexec_b64 s[36:37], s[6:7]
	s_cbranch_execz .LBB0_1187
	global_load_dwordx4 v[124:127], v[142:143], off
	s_branch .LBB0_1187
.LBB0_1192:
	s_or_b64 exec, exec, s[2:3]
	s_waitcnt vmcnt(0)
	v_mov_b32_e32 v132, v204
	v_mov_b32_e32 v133, v205
	v_mov_b32_e32 v134, v206
	v_mov_b32_e32 v135, v207
	ds_write_b128 v169, v[128:131] offset:13312
	s_and_saveexec_b64 s[2:3], s[6:7]
	s_cbranch_execz .LBB0_1011
	ds_write_b128 v167, v[124:127] offset:13312
	s_branch .LBB0_1011
